# LRU gate weight tiles converted by a direct per-thread transpose so the LDS tile loop takes 3 trips on every workgroup (was a 4th trip on 32 of them)
# speedup vs baseline: 1.0367x; 1.0005x over previous
; #define LAS __attribute__((address_space(3)))
; __device__ __forceinline__ unsigned cvtpk(float lo, float hi) { const f32x2 v = (f32x2){lo, hi}; const bf16v2 b = __builtin_convertvector(v, bf16v2); return __builtin_bit_cast(unsigned, b); }
; __device__ __forceinline__ WDesc wdesc(const Params& p, int l, int u) {
;     ...
;     { const int dir = v / 16, gate = (v / 8) % 2, h = v % 8; d.src = (gate ? p.in[8] : p.in[6]) + ((size_t)(l * 2 + dir) * 8 + h) * 4096; d.ldsrc = 64; d.c0 = 0; d.nvalid = 64; d.k0 = 0;
;       d.dst = (bf16_t*)(ws + WS_LRUW) + ((size_t)(dir * 2 + gate) * 8 + h) * 4096; d.lddst = 64; d.r0 = 0; return d; }
; __device__ void phase_weights(const Params& p, int l, LAS unsigned char* lds) {
;     ...
;         { const int r = tid >> 3, kg = (tid & 7) * 8;
; #pragma unroll
;           for (int j = 0; j < 4; ++j) { const int u = u0 + j * G;
;               if (u < TOT) { const WDesc d = wdesc(p, l, u); const LAS float* Tj = T + j * 4160; u32x4 w;
;                   w.x = cvtpk(Tj[(kg + 0) * 65 + r], Tj[(kg + 1) * 65 + r]); w.y = cvtpk(Tj[(kg + 2) * 65 + r], Tj[(kg + 3) * 65 + r]);
;                   w.z = cvtpk(Tj[(kg + 4) * 65 + r], Tj[(kg + 5) * 65 + r]); w.w = cvtpk(Tj[(kg + 6) * 65 + r], Tj[(kg + 7) * 65 + r]);
;                   *(u32x4*)(d.dst + (size_t)(d.r0 + r) * d.lddst + d.k0 + kg) = w; } } }
.LBB0_377:
	s_cmpk_gt_u32 s2, 0x7f
	s_cbranch_scc1 .Llruw_done
	v_readlane_b32 s4, v254, 39
	v_readlane_b32 s5, v254, 40
	v_readlane_b32 s8, v254, 43
	v_readlane_b32 s9, v254, 44
	v_readlane_b32 s26, v255, 16
	v_lshrrev_b32_e32 v1, 6, v245
	v_and_b32_e32 v2, 63, v245
	s_lshr_b32 s0, s2, 2
	s_and_b32 s1, s2, 3
	s_bitcmp1_b32 s0, 3
	s_cselect_b32 s4, s8, s4
	s_cselect_b32 s5, s9, s5
	s_lshr_b32 s10, s0, 4
	s_lshl_b32 s11, s26, 1
	s_add_u32 s11, s11, s10
	s_lshl_b32 s11, s11, 3
	s_and_b32 s10, s0, 7
	s_add_u32 s11, s11, s10
	s_lshl_b32 s11, s11, 14
	s_add_u32 s4, s4, s11
	s_addc_u32 s5, s5, 0
	v_lshl_add_u32 v1, s1, 3, v1
	v_lshlrev_b32_e32 v3, 9, v1
	v_lshl_add_u32 v3, v2, 2, v3
	global_load_dword v4, v3, s[4:5]
	global_load_dword v5, v3, s[4:5] offset:256
	v_readlane_b32 s8, v254, 17
	v_readlane_b32 s9, v254, 18
	v_lshlrev_b32_e32 v6, 7, v2
	v_lshl_add_u32 v6, v1, 2, v6
	s_lshl_b32 s10, s0, 13
	s_add_u32 s8, s8, s10
	s_addc_u32 s9, s9, 0
	s_waitcnt vmcnt(0)
	v_cvt_pk_bf16_f32 v4, v4, v5
	global_store_dword v6, v4, s[8:9]

; #define LAS __attribute__((address_space(3)))
; __device__ __forceinline__ unsigned cvtpk(float lo, float hi) { const f32x2 v = (f32x2){lo, hi}; const bf16v2 b = __builtin_convertvector(v, bf16v2); return __builtin_bit_cast(unsigned, b); }
; __device__ __forceinline__ int obid() { int t = blockIdx.x; asm volatile("" : "+s"(t)); return t; }
; __device__ void phase_weights(const Params& p, int l, LAS unsigned char* lds) {
;     ...
;     for (int u0 = obid(); u0 < TOT; u0 += 4 * G) {
;         f32x4 v[4][2];
;         { const int k = tid >> 3, cg8 = (tid & 7) * 8;
; #pragma unroll
;           for (int j = 0; j < 4; ++j) { const int u = u0 + j * G; v[j][0] = (f32x4){0.f, 0.f, 0.f, 0.f}; v[j][1] = v[j][0];
;               if (u < TOT) { const WDesc d = wdesc(p, l, u); const float* sp = d.src + (size_t)(d.k0 + k) * d.ldsrc + d.c0 + cg8;
;                   if (cg8 + 3 < d.nvalid) v[j][0] = __builtin_nontemporal_load((const f32x4*)sp); if (cg8 + 7 < d.nvalid) v[j][1] = __builtin_nontemporal_load((const f32x4*)(sp + 4)); } }
; #pragma unroll
;           for (int j = 0; j < 4; ++j)
; #pragma unroll
;               for (int i = 0; i < 2; ++i) { LAS float* Tj = T + j * 4160 + k * 65 + cg8 + 4 * i; Tj[0] = v[j][i][0]; Tj[1] = v[j][i][1]; Tj[2] = v[j][i][2]; Tj[3] = v[j][i][3]; } }
;         __syncthreads();
;         { const int r = tid >> 3, kg = (tid & 7) * 8;
; #pragma unroll
;           for (int j = 0; j < 4; ++j) { const int u = u0 + j * G;
;               if (u < TOT) { const WDesc d = wdesc(p, l, u); const LAS float* Tj = T + j * 4160; u32x4 w;
;                   w.x = cvtpk(Tj[(kg + 0) * 65 + r], Tj[(kg + 1) * 65 + r]); w.y = cvtpk(Tj[(kg + 2) * 65 + r], Tj[(kg + 3) * 65 + r]);
;                   w.z = cvtpk(Tj[(kg + 4) * 65 + r], Tj[(kg + 5) * 65 + r]); w.w = cvtpk(Tj[(kg + 6) * 65 + r], Tj[(kg + 7) * 65 + r]);
;                   *(u32x4*)(d.dst + (size_t)(d.r0 + r) * d.lddst + d.k0 + kg) = w; } } }
;         __syncthreads();
;     }
.LBB0_382:
	s_add_i32 s27, s27, s31
	s_add_i32 s38, s38, s39
	s_add_i32 s40, s40, s41
	s_add_i32 s43, s43, s44
	s_cmpk_gt_i32 s27, 0xbff
	s_barrier
	s_cbranch_scc1 .LBB0_538
